# in-proj q/u epilogue heads: the eight row-sum loads issued together (one round trip instead of eight)
# baseline (speedup 1.0000x reference)
.LBB0_602:
	s_cmp_lg_u32 s42, 2
	s_mov_b64 s[42:43], -1
	s_cbranch_scc0 .LBB0_604
	v_lshlrev_b64 v[130:131], 10, v[190:191]
	v_lshl_add_u64 v[130:131], s[34:35], 0, v[130:131]
	s_add_i32 s42, s6, 0xfffffd00
	s_mov_b32 s43, s55
	v_lshl_add_u64 v[130:131], s[42:43], 1, v[130:131]
	s_lshl_b32 s42, s76, 1
	v_lshl_add_u64 v[130:131], v[130:131], 0, s[42:43]
	v_lshlrev_b32_e32 v132, 1, v217
	v_mov_b32_e32 v133, v1
	v_lshl_add_u64 v[146:147], v[130:131], 0, v[132:133]
	global_load_dwordx4 v[130:133], v[188:189], off
	global_load_dwordx4 v[134:137], v[188:189], off offset:256
	global_load_dwordx4 v[138:141], v[188:189], off offset:512
	global_load_dwordx4 v[142:145], v[188:189], off offset:768
	global_load_dwordx4 v[168:171], v[188:189], off offset:2048
	global_load_dwordx4 v[172:175], v[188:189], off offset:2304
	global_load_dwordx4 v[228:231], v[188:189], off offset:2560
	global_load_dwordx4 v[232:235], v[188:189], off offset:2816
	v_mov_b64_e32 v[164:165], 0
	v_mov_b64_e32 v[166:167], v[146:147]
	s_movk_i32 s5, 0x4000
	s_waitcnt vmcnt(7)
	v_mov_b32_e32 v212, v131
	v_mov_b32_e32 v213, v132
	v_mov_b32_e32 v131, v133
	v_pk_add_f32 v[130:131], v[212:213], v[130:131]
	s_nop 0
	v_add_f32_e32 v130, v130, v131
	v_fmamk_f32 v130, v130, 0x3a800000, v223
	v_rsq_f32_e32 v162, v130
	s_waitcnt vmcnt(6)
	v_mov_b32_e32 v212, v135
	v_mov_b32_e32 v213, v136
	v_mov_b32_e32 v135, v137
	v_pk_add_f32 v[134:135], v[212:213], v[134:135]
	s_nop 0
	v_add_f32_e32 v134, v134, v135
	v_fmamk_f32 v134, v134, 0x3a800000, v223
	v_rsq_f32_e32 v160, v134
	s_waitcnt vmcnt(5)
	v_mov_b32_e32 v212, v139
	v_mov_b32_e32 v213, v140
	v_mov_b32_e32 v139, v141
	v_pk_add_f32 v[138:139], v[212:213], v[138:139]
	s_nop 0
	v_add_f32_e32 v138, v138, v139
	v_fmamk_f32 v138, v138, 0x3a800000, v223
	v_rsq_f32_e32 v152, v138
	s_waitcnt vmcnt(4)
	v_mov_b32_e32 v212, v143
	v_mov_b32_e32 v213, v144
	v_mov_b32_e32 v143, v145
	v_pk_add_f32 v[142:143], v[212:213], v[142:143]
	s_nop 0
	v_add_f32_e32 v142, v142, v143
	v_fmamk_f32 v142, v142, 0x3a800000, v223
	v_rsq_f32_e32 v158, v142
	s_waitcnt vmcnt(3)
	v_mov_b32_e32 v212, v169
	v_mov_b32_e32 v213, v170
	v_mov_b32_e32 v169, v171
	v_pk_add_f32 v[168:169], v[212:213], v[168:169]
	s_nop 0
	v_add_f32_e32 v168, v168, v169
	v_fmamk_f32 v168, v168, 0x3a800000, v223
	v_rsq_f32_e32 v154, v168
	s_waitcnt vmcnt(2)
	v_mov_b32_e32 v212, v173
	v_mov_b32_e32 v213, v174
	v_mov_b32_e32 v173, v175
	v_pk_add_f32 v[172:173], v[212:213], v[172:173]
	s_nop 0
	v_add_f32_e32 v172, v172, v173
	v_fmamk_f32 v172, v172, 0x3a800000, v223
	v_rsq_f32_e32 v150, v172
	s_waitcnt vmcnt(1)
	v_mov_b32_e32 v212, v229
	v_mov_b32_e32 v213, v230
	v_mov_b32_e32 v229, v231
	v_pk_add_f32 v[228:229], v[212:213], v[228:229]
	s_nop 0
	v_add_f32_e32 v228, v228, v229
	v_fmamk_f32 v228, v228, 0x3a800000, v223
	v_rsq_f32_e32 v148, v228
	s_waitcnt vmcnt(0)
	v_mov_b32_e32 v212, v233
	v_mov_b32_e32 v213, v234
	v_mov_b32_e32 v233, v235
	v_pk_add_f32 v[232:233], v[212:213], v[232:233]
	s_nop 0
	v_add_f32_e32 v232, v232, v233
	v_fmamk_f32 v232, v232, 0x3a800000, v223
	v_rsq_f32_e32 v156, v232
	global_load_dwordx4 v[142:145], v[186:187], off
	global_load_dwordx4 v[138:141], v[186:187], off offset:64
	global_load_dwordx4 v[134:137], v[186:187], off offset:512
	global_load_dwordx4 v[130:133], v[186:187], off offset:576
	s_waitcnt vmcnt(3)
	v_pk_fma_f32 v[168:169], v[126:127], v[162:163], v[142:143] op_sel_hi:[1,0,1]
	v_pk_fma_f32 v[164:165], v[128:129], v[162:163], v[144:145] op_sel_hi:[1,0,1]
	s_waitcnt vmcnt(2)
	v_pk_fma_f32 v[170:171], v[124:125], v[162:163], v[140:141] op_sel_hi:[1,0,1]
	v_pk_fma_f32 v[172:173], v[122:123], v[162:163], v[138:139] op_sel_hi:[1,0,1]
	s_waitcnt vmcnt(1)
	v_pk_fma_f32 v[174:175], v[120:121], v[162:163], v[136:137] op_sel_hi:[1,0,1]
	v_pk_fma_f32 v[176:177], v[118:119], v[162:163], v[134:135] op_sel_hi:[1,0,1]
	s_waitcnt vmcnt(0)
	v_pk_fma_f32 v[192:193], v[116:117], v[162:163], v[132:133] op_sel_hi:[1,0,1]
	v_pk_fma_f32 v[162:163], v[114:115], v[162:163], v[130:131] op_sel_hi:[1,0,1]
	v_cvt_pk_bf16_f32 v240, v168, v169
	v_cvt_pk_bf16_f32 v241, v164, v165
	v_mbcnt_lo_u32_b32 v0, -1, 0
	v_mbcnt_hi_u32_b32 v0, -1, v0
	v_bfe_u32 v0, v0, 4, 1
	v_mul_u32_u24_e32 v0, 24, v0
	v_lshl_add_u64 v[248:249], v[166:167], 0, v[0:1]
	v_cvt_pk_bf16_f32 v242, v172, v173
	v_cvt_pk_bf16_f32 v243, v170, v171
	s_nop 1
	v_permlane16_swap_b32_e32 v240, v242
	v_permlane16_swap_b32_e32 v241, v243
	global_store_dwordx4 v[248:249], v[240:243], off
	v_cvt_pk_bf16_f32 v244, v176, v177
	v_cvt_pk_bf16_f32 v245, v174, v175
	s_nop 0
	v_cvt_pk_bf16_f32 v246, v162, v163
	v_cvt_pk_bf16_f32 v247, v192, v193
	s_nop 1
	v_permlane16_swap_b32_e32 v244, v246
	v_permlane16_swap_b32_e32 v245, v247
	global_store_dwordx4 v[248:249], v[244:247], off offset:64
	v_mov_b64_e32 v[162:163], 0
	v_mov_b64_e32 v[164:165], v[146:147]
	v_pk_fma_f32 v[166:167], v[110:111], v[160:161], v[142:143] op_sel_hi:[1,0,1]
	v_pk_fma_f32 v[162:163], v[112:113], v[160:161], v[144:145] op_sel_hi:[1,0,1]
	v_cvt_pk_bf16_f32 v240, v166, v167
	v_pk_fma_f32 v[168:169], v[108:109], v[160:161], v[140:141] op_sel_hi:[1,0,1]
	v_cvt_pk_bf16_f32 v241, v162, v163
	v_add_co_u32_e32 v162, vcc, s5, v164
	v_pk_fma_f32 v[170:171], v[106:107], v[160:161], v[138:139] op_sel_hi:[1,0,1]
	s_nop 0
	v_addc_co_u32_e32 v163, vcc, 0, v165, vcc
	v_pk_fma_f32 v[172:173], v[104:105], v[160:161], v[136:137] op_sel_hi:[1,0,1]
	v_pk_fma_f32 v[174:175], v[102:103], v[160:161], v[134:135] op_sel_hi:[1,0,1]
	v_pk_fma_f32 v[176:177], v[100:101], v[160:161], v[132:133] op_sel_hi:[1,0,1]
	v_pk_fma_f32 v[160:161], v[98:99], v[160:161], v[130:131] op_sel_hi:[1,0,1]
	v_mbcnt_lo_u32_b32 v0, -1, 0
	v_mbcnt_hi_u32_b32 v0, -1, v0
	v_bfe_u32 v0, v0, 4, 1
	v_mul_u32_u24_e32 v0, 24, v0
	v_lshl_add_u64 v[248:249], v[162:163], 0, v[0:1]
	v_cvt_pk_bf16_f32 v242, v170, v171
	v_cvt_pk_bf16_f32 v243, v168, v169
	s_nop 1
	v_permlane16_swap_b32_e32 v240, v242
	v_permlane16_swap_b32_e32 v241, v243
	global_store_dwordx4 v[248:249], v[240:243], off
	v_cvt_pk_bf16_f32 v244, v174, v175
	v_cvt_pk_bf16_f32 v245, v172, v173
	s_nop 0
	v_cvt_pk_bf16_f32 v246, v160, v161
	v_cvt_pk_bf16_f32 v247, v176, v177
	s_nop 1
	v_permlane16_swap_b32_e32 v244, v246
	v_permlane16_swap_b32_e32 v245, v247
	global_store_dwordx4 v[248:249], v[244:247], off offset:64
	v_mov_b64_e32 v[160:161], 0
	v_mov_b64_e32 v[162:163], v[146:147]
	v_pk_fma_f32 v[164:165], v[94:95], v[152:153], v[142:143] op_sel_hi:[1,0,1]
	v_pk_fma_f32 v[160:161], v[96:97], v[152:153], v[144:145] op_sel_hi:[1,0,1]
	s_mov_b32 s5, 0x8000
	v_cvt_pk_bf16_f32 v240, v164, v165
	v_cvt_pk_bf16_f32 v241, v160, v161
	v_add_co_u32_e32 v160, vcc, s5, v162
	v_pk_fma_f32 v[166:167], v[92:93], v[152:153], v[140:141] op_sel_hi:[1,0,1]
	s_nop 0
	v_addc_co_u32_e32 v161, vcc, 0, v163, vcc
	v_pk_fma_f32 v[168:169], v[90:91], v[152:153], v[138:139] op_sel_hi:[1,0,1]
	v_pk_fma_f32 v[170:171], v[88:89], v[152:153], v[136:137] op_sel_hi:[1,0,1]
	v_pk_fma_f32 v[172:173], v[86:87], v[152:153], v[134:135] op_sel_hi:[1,0,1]
	v_pk_fma_f32 v[174:175], v[84:85], v[152:153], v[132:133] op_sel_hi:[1,0,1]
	v_pk_fma_f32 v[152:153], v[82:83], v[152:153], v[130:131] op_sel_hi:[1,0,1]
	v_mbcnt_lo_u32_b32 v0, -1, 0
	v_mbcnt_hi_u32_b32 v0, -1, v0
	v_bfe_u32 v0, v0, 4, 1
	v_mul_u32_u24_e32 v0, 24, v0
	v_lshl_add_u64 v[248:249], v[160:161], 0, v[0:1]
	v_cvt_pk_bf16_f32 v242, v168, v169
	v_cvt_pk_bf16_f32 v243, v166, v167
	s_nop 1
	v_permlane16_swap_b32_e32 v240, v242
	v_permlane16_swap_b32_e32 v241, v243
	global_store_dwordx4 v[248:249], v[240:243], off
	v_cvt_pk_bf16_f32 v244, v172, v173
	v_cvt_pk_bf16_f32 v245, v170, v171
	s_nop 0
	v_cvt_pk_bf16_f32 v246, v152, v153
	v_cvt_pk_bf16_f32 v247, v174, v175
	s_nop 1
	v_permlane16_swap_b32_e32 v244, v246
	v_permlane16_swap_b32_e32 v245, v247
	global_store_dwordx4 v[248:249], v[244:247], off offset:64
	v_mov_b64_e32 v[152:153], 0
	v_mov_b64_e32 v[160:161], v[146:147]
	v_pk_fma_f32 v[162:163], v[78:79], v[158:159], v[142:143] op_sel_hi:[1,0,1]
	v_pk_fma_f32 v[152:153], v[80:81], v[158:159], v[144:145] op_sel_hi:[1,0,1]
	s_mov_b32 s5, 0xc000
	v_cvt_pk_bf16_f32 v240, v162, v163
	v_cvt_pk_bf16_f32 v241, v152, v153
	v_add_co_u32_e32 v152, vcc, s5, v160
	v_pk_fma_f32 v[164:165], v[76:77], v[158:159], v[140:141] op_sel_hi:[1,0,1]
	s_nop 0
	v_addc_co_u32_e32 v153, vcc, 0, v161, vcc
	v_pk_fma_f32 v[166:167], v[74:75], v[158:159], v[138:139] op_sel_hi:[1,0,1]
	v_pk_fma_f32 v[168:169], v[72:73], v[158:159], v[136:137] op_sel_hi:[1,0,1]
	v_pk_fma_f32 v[170:171], v[70:71], v[158:159], v[134:135] op_sel_hi:[1,0,1]
	v_pk_fma_f32 v[172:173], v[68:69], v[158:159], v[132:133] op_sel_hi:[1,0,1]
	v_pk_fma_f32 v[158:159], v[66:67], v[158:159], v[130:131] op_sel_hi:[1,0,1]
	v_mbcnt_lo_u32_b32 v0, -1, 0
	v_mbcnt_hi_u32_b32 v0, -1, v0
	v_bfe_u32 v0, v0, 4, 1
	v_mul_u32_u24_e32 v0, 24, v0
	v_lshl_add_u64 v[248:249], v[152:153], 0, v[0:1]
	v_cvt_pk_bf16_f32 v242, v166, v167
	v_cvt_pk_bf16_f32 v243, v164, v165
	s_nop 1
	v_permlane16_swap_b32_e32 v240, v242
	v_permlane16_swap_b32_e32 v241, v243
	global_store_dwordx4 v[248:249], v[240:243], off
	v_cvt_pk_bf16_f32 v244, v170, v171
	v_cvt_pk_bf16_f32 v245, v168, v169
	s_nop 0
	v_cvt_pk_bf16_f32 v246, v158, v159
	v_cvt_pk_bf16_f32 v247, v172, v173
	s_nop 1
	v_permlane16_swap_b32_e32 v244, v246
	v_permlane16_swap_b32_e32 v245, v247
	global_store_dwordx4 v[248:249], v[244:247], off offset:64
	v_mov_b64_e32 v[152:153], 0
	v_mov_b64_e32 v[158:159], v[146:147]
	v_pk_fma_f32 v[160:161], v[62:63], v[154:155], v[142:143] op_sel_hi:[1,0,1]
	v_pk_fma_f32 v[152:153], v[64:65], v[154:155], v[144:145] op_sel_hi:[1,0,1]
	s_mov_b32 s5, 0x20000
	v_cvt_pk_bf16_f32 v240, v160, v161
	v_cvt_pk_bf16_f32 v241, v152, v153
	v_add_co_u32_e32 v152, vcc, s5, v158
	v_pk_fma_f32 v[162:163], v[60:61], v[154:155], v[140:141] op_sel_hi:[1,0,1]
	s_nop 0
	v_addc_co_u32_e32 v153, vcc, 0, v159, vcc
	v_pk_fma_f32 v[164:165], v[58:59], v[154:155], v[138:139] op_sel_hi:[1,0,1]
	v_pk_fma_f32 v[166:167], v[56:57], v[154:155], v[136:137] op_sel_hi:[1,0,1]
	v_pk_fma_f32 v[168:169], v[54:55], v[154:155], v[134:135] op_sel_hi:[1,0,1]
	v_pk_fma_f32 v[170:171], v[52:53], v[154:155], v[132:133] op_sel_hi:[1,0,1]
	v_pk_fma_f32 v[154:155], v[50:51], v[154:155], v[130:131] op_sel_hi:[1,0,1]
	v_mbcnt_lo_u32_b32 v0, -1, 0
	v_mbcnt_hi_u32_b32 v0, -1, v0
	v_bfe_u32 v0, v0, 4, 1
	v_mul_u32_u24_e32 v0, 24, v0
	v_lshl_add_u64 v[248:249], v[152:153], 0, v[0:1]
	v_cvt_pk_bf16_f32 v242, v164, v165
	v_cvt_pk_bf16_f32 v243, v162, v163
	s_nop 1
	v_permlane16_swap_b32_e32 v240, v242
	v_permlane16_swap_b32_e32 v241, v243
	global_store_dwordx4 v[248:249], v[240:243], off
	v_cvt_pk_bf16_f32 v244, v168, v169
	v_cvt_pk_bf16_f32 v245, v166, v167
	s_nop 0
	v_cvt_pk_bf16_f32 v246, v154, v155
	v_cvt_pk_bf16_f32 v247, v170, v171
	s_nop 1
	v_permlane16_swap_b32_e32 v244, v246
	v_permlane16_swap_b32_e32 v245, v247
	global_store_dwordx4 v[248:249], v[244:247], off offset:64
	v_mov_b64_e32 v[152:153], 0
	v_mov_b64_e32 v[154:155], v[146:147]
	v_pk_fma_f32 v[158:159], v[46:47], v[150:151], v[142:143] op_sel_hi:[1,0,1]
	v_pk_fma_f32 v[152:153], v[48:49], v[150:151], v[144:145] op_sel_hi:[1,0,1]
	s_mov_b32 s5, 0x24000
	v_cvt_pk_bf16_f32 v240, v158, v159
	v_cvt_pk_bf16_f32 v241, v152, v153
	v_add_co_u32_e32 v152, vcc, s5, v154
	v_pk_fma_f32 v[160:161], v[44:45], v[150:151], v[140:141] op_sel_hi:[1,0,1]
	s_nop 0
	v_addc_co_u32_e32 v153, vcc, 0, v155, vcc
	v_pk_fma_f32 v[162:163], v[42:43], v[150:151], v[138:139] op_sel_hi:[1,0,1]
	v_pk_fma_f32 v[164:165], v[40:41], v[150:151], v[136:137] op_sel_hi:[1,0,1]
	v_pk_fma_f32 v[166:167], v[38:39], v[150:151], v[134:135] op_sel_hi:[1,0,1]
	v_pk_fma_f32 v[168:169], v[36:37], v[150:151], v[132:133] op_sel_hi:[1,0,1]
	v_pk_fma_f32 v[150:151], v[34:35], v[150:151], v[130:131] op_sel_hi:[1,0,1]
	v_mbcnt_lo_u32_b32 v0, -1, 0
	v_mbcnt_hi_u32_b32 v0, -1, v0
	v_bfe_u32 v0, v0, 4, 1
	v_mul_u32_u24_e32 v0, 24, v0
	v_lshl_add_u64 v[248:249], v[152:153], 0, v[0:1]
	v_cvt_pk_bf16_f32 v242, v162, v163
	v_cvt_pk_bf16_f32 v243, v160, v161
	s_nop 1
	v_permlane16_swap_b32_e32 v240, v242
	v_permlane16_swap_b32_e32 v241, v243
	global_store_dwordx4 v[248:249], v[240:243], off
	v_cvt_pk_bf16_f32 v244, v166, v167
	v_cvt_pk_bf16_f32 v245, v164, v165
	s_nop 0
	v_cvt_pk_bf16_f32 v246, v150, v151
	v_cvt_pk_bf16_f32 v247, v168, v169
	s_nop 1
	v_permlane16_swap_b32_e32 v244, v246
	v_permlane16_swap_b32_e32 v245, v247
	global_store_dwordx4 v[248:249], v[244:247], off offset:64
	v_mov_b64_e32 v[150:151], 0
	v_mov_b64_e32 v[152:153], v[146:147]
	v_pk_fma_f32 v[154:155], v[30:31], v[148:149], v[142:143] op_sel_hi:[1,0,1]
	v_pk_fma_f32 v[150:151], v[32:33], v[148:149], v[144:145] op_sel_hi:[1,0,1]
	s_mov_b32 s5, 0x28000
	v_cvt_pk_bf16_f32 v240, v154, v155
	v_cvt_pk_bf16_f32 v241, v150, v151
	v_add_co_u32_e32 v150, vcc, s5, v152
	v_pk_fma_f32 v[158:159], v[28:29], v[148:149], v[140:141] op_sel_hi:[1,0,1]
	s_nop 0
	v_addc_co_u32_e32 v151, vcc, 0, v153, vcc
	v_pk_fma_f32 v[160:161], v[26:27], v[148:149], v[138:139] op_sel_hi:[1,0,1]
	v_mbcnt_lo_u32_b32 v0, -1, 0
	v_mbcnt_hi_u32_b32 v0, -1, v0
	v_bfe_u32 v0, v0, 4, 1
	v_mul_u32_u24_e32 v0, 24, v0
	v_lshl_add_u64 v[248:249], v[150:151], 0, v[0:1]
	v_cvt_pk_bf16_f32 v242, v160, v161
	v_cvt_pk_bf16_f32 v243, v158, v159
	v_pk_fma_f32 v[162:163], v[24:25], v[148:149], v[136:137] op_sel_hi:[1,0,1]
	v_pk_fma_f32 v[164:165], v[22:23], v[148:149], v[134:135] op_sel_hi:[1,0,1]
	s_nop 1
	v_permlane16_swap_b32_e32 v240, v242
	v_permlane16_swap_b32_e32 v241, v243
	global_store_dwordx4 v[248:249], v[240:243], off
	v_cvt_pk_bf16_f32 v244, v164, v165
	v_cvt_pk_bf16_f32 v245, v162, v163
	v_pk_fma_f32 v[166:167], v[20:21], v[148:149], v[132:133] op_sel_hi:[1,0,1]
	v_pk_fma_f32 v[168:169], v[18:19], v[148:149], v[130:131] op_sel_hi:[1,0,1]
	s_nop 0
	v_cvt_pk_bf16_f32 v246, v168, v169
	v_cvt_pk_bf16_f32 v247, v166, v167
	s_nop 1
	v_permlane16_swap_b32_e32 v244, v246
	v_permlane16_swap_b32_e32 v245, v247
	global_store_dwordx4 v[248:249], v[244:247], off offset:64
	v_mov_b64_e32 v[150:151], 0
	v_pk_fma_f32 v[144:145], v[16:17], v[156:157], v[144:145] op_sel_hi:[1,0,1]
	v_pk_fma_f32 v[142:143], v[14:15], v[156:157], v[142:143] op_sel_hi:[1,0,1]
	s_mov_b32 s5, 0x2c000
	v_cvt_pk_bf16_f32 v240, v142, v143
	v_cvt_pk_bf16_f32 v241, v144, v145
	v_pk_fma_f32 v[138:139], v[10:11], v[156:157], v[138:139] op_sel_hi:[1,0,1]
	v_add_co_u32_e32 v144, vcc, s5, v146
	v_pk_fma_f32 v[134:135], v[6:7], v[156:157], v[134:135] op_sel_hi:[1,0,1]
	v_pk_fma_f32 v[130:131], v[2:3], v[156:157], v[130:131] op_sel_hi:[1,0,1]
	v_addc_co_u32_e32 v145, vcc, 0, v147, vcc
	v_pk_fma_f32 v[140:141], v[12:13], v[156:157], v[140:141] op_sel_hi:[1,0,1]
	v_pk_fma_f32 v[136:137], v[8:9], v[156:157], v[136:137] op_sel_hi:[1,0,1]
	v_pk_fma_f32 v[132:133], v[4:5], v[156:157], v[132:133] op_sel_hi:[1,0,1]
	v_mbcnt_lo_u32_b32 v0, -1, 0
	v_mbcnt_hi_u32_b32 v0, -1, v0
	v_bfe_u32 v0, v0, 4, 1
	v_mul_u32_u24_e32 v0, 24, v0
	v_lshl_add_u64 v[248:249], v[144:145], 0, v[0:1]
	v_cvt_pk_bf16_f32 v242, v138, v139
	v_cvt_pk_bf16_f32 v243, v140, v141
	s_nop 1
	v_permlane16_swap_b32_e32 v240, v242
	v_permlane16_swap_b32_e32 v241, v243
	global_store_dwordx4 v[248:249], v[240:243], off
	v_cvt_pk_bf16_f32 v244, v134, v135
	v_cvt_pk_bf16_f32 v245, v136, v137
	s_nop 0
	v_cvt_pk_bf16_f32 v246, v130, v131
	v_cvt_pk_bf16_f32 v247, v132, v133
	s_nop 1
	v_permlane16_swap_b32_e32 v244, v246
	v_permlane16_swap_b32_e32 v245, v247
	global_store_dwordx4 v[248:249], v[244:247], off offset:64
	s_mov_b64 s[42:43], 0

.LBB0_660:
	v_lshlrev_b64 v[130:131], 10, v[190:191]
	s_or_b32 s4, s6, s76
	v_lshl_add_u64 v[130:131], s[36:37], 0, v[130:131]
	s_ashr_i32 s5, s4, 31
	v_lshl_add_u64 v[130:131], s[4:5], 1, v[130:131]
	v_lshlrev_b32_e32 v132, 1, v217
	v_mov_b32_e32 v133, v1
	v_lshl_add_u64 v[162:163], v[130:131], 0, v[132:133]
	global_load_dwordx4 v[130:133], v[188:189], off
	global_load_dwordx4 v[134:137], v[188:189], off offset:256
	global_load_dwordx4 v[138:141], v[188:189], off offset:512
	global_load_dwordx4 v[142:145], v[188:189], off offset:768
	global_load_dwordx4 v[146:149], v[188:189], off offset:2048
	global_load_dwordx4 v[150:153], v[188:189], off offset:2304
	global_load_dwordx4 v[154:157], v[188:189], off offset:2560
	global_load_dwordx4 v[158:161], v[188:189], off offset:2816
	v_mov_b64_e32 v[192:193], 0
	v_or_b32_e32 v165, 1, v217
	v_or_b32_e32 v167, 2, v217
	v_or_b32_e32 v169, 3, v217
	v_cvt_f32_ubyte0_e32 v165, v165
	v_cvt_f32_ubyte0_e32 v167, v167
	v_cvt_f32_ubyte0_e32 v169, v169
	v_mul_f32_e32 v165, 0xbf549a78, v165
	v_mul_f32_e32 v167, 0xbf549a78, v167
	v_mul_f32_e32 v169, 0xbf549a78, v169
	v_exp_f32_e32 v165, v165
	v_exp_f32_e32 v167, v167
	v_exp_f32_e32 v169, v169
	v_cndmask_b32_e64 v171, 0, 1, s[2:3]
	v_mul_f32_e32 v165, 0.15915494, v165
	v_mul_f32_e32 v167, 0.15915494, v167
	v_mul_f32_e32 v169, 0.15915494, v169
	v_cmp_ne_u32_e64 s[42:43], 1, v171
	s_andn2_b64 vcc, exec, s[2:3]
	s_waitcnt vmcnt(7)
	v_mov_b32_e32 v212, v131
	v_mov_b32_e32 v213, v132
	v_mov_b32_e32 v131, v133
	v_pk_add_f32 v[130:131], v[212:213], v[130:131]
	s_nop 0
	v_add_f32_e32 v130, v130, v131
	v_fmamk_f32 v130, v130, 0x3a800000, v223
	v_rsq_f32_e32 v190, v130
	s_waitcnt vmcnt(6)
	v_mov_b32_e32 v212, v135
	v_mov_b32_e32 v213, v136
	v_mov_b32_e32 v135, v137
	v_pk_add_f32 v[134:135], v[212:213], v[134:135]
	s_nop 0
	v_add_f32_e32 v134, v134, v135
	v_fmamk_f32 v134, v134, 0x3a800000, v223
	v_rsq_f32_e32 v176, v134
	s_waitcnt vmcnt(5)
	v_mov_b32_e32 v212, v139
	v_mov_b32_e32 v213, v140
	v_mov_b32_e32 v139, v141
	v_pk_add_f32 v[138:139], v[212:213], v[138:139]
	s_nop 0
	v_add_f32_e32 v138, v138, v139
	v_fmamk_f32 v138, v138, 0x3a800000, v223
	v_rsq_f32_e32 v174, v138
	s_waitcnt vmcnt(4)
	v_mov_b32_e32 v212, v143
	v_mov_b32_e32 v213, v144
	v_mov_b32_e32 v143, v145
	v_pk_add_f32 v[142:143], v[212:213], v[142:143]
	s_nop 0
	v_add_f32_e32 v142, v142, v143
	v_fmamk_f32 v142, v142, 0x3a800000, v223
	v_rsq_f32_e32 v172, v142
	s_waitcnt vmcnt(3)
	v_add_f32_e32 v146, v146, v147
	v_add_f32_e32 v147, v148, v149
	v_add_f32_e32 v146, v146, v147
	v_fmamk_f32 v146, v146, 0x3a800000, v223
	v_rsq_f32_e32 v170, v146
	s_waitcnt vmcnt(2)
	v_add_f32_e32 v150, v150, v151
	v_add_f32_e32 v151, v152, v153
	v_add_f32_e32 v150, v150, v151
	v_fmamk_f32 v150, v150, 0x3a800000, v223
	v_rsq_f32_e32 v168, v150
	s_waitcnt vmcnt(1)
	v_add_f32_e32 v154, v154, v155
	v_add_f32_e32 v155, v156, v157
	v_add_f32_e32 v154, v154, v155
	v_fmamk_f32 v154, v154, 0x3a800000, v223
	v_rsq_f32_e32 v166, v154
	v_and_b32_e32 v189, 63, v216
	v_cvt_f32_ubyte0_e32 v171, v189
	v_mul_f32_e32 v177, v165, v171
	v_mul_f32_e32 v175, v167, v171
	s_waitcnt vmcnt(0)
	v_add_f32_e32 v158, v158, v159
	v_add_f32_e32 v159, v160, v161
	v_add_f32_e32 v158, v158, v159
	v_fmamk_f32 v158, v158, 0x3a800000, v223
	v_rsq_f32_e32 v164, v158
	global_load_dwordx4 v[158:161], v[186:187], off
	global_load_dwordx4 v[154:157], v[186:187], off offset:64
	global_load_dwordx4 v[150:153], v[186:187], off offset:512
	global_load_dwordx4 v[146:149], v[186:187], off offset:576
	global_load_dwordx4 v[142:145], v0, s[24:25]
	global_load_dwordx4 v[138:141], v0, s[24:25] offset:64
	global_load_dwordx4 v[134:137], v0, s[24:25] offset:128
	global_load_dwordx4 v[130:133], v0, s[24:25] offset:192
	v_mov_b64_e32 v[186:187], v[162:163]
	v_cvt_f32_ubyte0_e32 v0, v217
	v_mul_f32_e32 v0, 0xbf549a78, v0
	v_exp_f32_e32 v0, v0
	s_waitcnt vmcnt(7)
	v_pk_fma_f32 v[128:129], v[128:129], v[190:191], v[160:161] op_sel_hi:[1,0,1]
	v_pk_fma_f32 v[126:127], v[126:127], v[190:191], v[158:159] op_sel_hi:[1,0,1]
	s_waitcnt vmcnt(6)
	v_pk_fma_f32 v[124:125], v[124:125], v[190:191], v[156:157] op_sel_hi:[1,0,1]
	s_waitcnt vmcnt(4)
	v_pk_fma_f32 v[194:195], v[116:117], v[190:191], v[148:149] op_sel_hi:[1,0,1]
	v_mul_f32_e32 v116, v127, v127
	v_mul_f32_e32 v117, v129, v129
	v_pk_fma_f32 v[122:123], v[122:123], v[190:191], v[154:155] op_sel_hi:[1,0,1]
	v_fmac_f32_e32 v116, v126, v126
	v_fmac_f32_e32 v117, v128, v128
	v_pk_fma_f32 v[192:193], v[120:121], v[190:191], v[152:153] op_sel_hi:[1,0,1]
	v_add_f32_e32 v116, v116, v117
	v_mul_f32_e32 v117, v123, v123
	v_mul_f32_e32 v120, v125, v125
	v_fmac_f32_e32 v117, v122, v122
	v_fmac_f32_e32 v120, v124, v124
	v_pk_fma_f32 v[118:119], v[118:119], v[190:191], v[150:151] op_sel_hi:[1,0,1]
	v_add_f32_e32 v117, v117, v120
	v_add_f32_e32 v116, v116, v117
	v_mul_f32_e32 v117, v119, v119
	v_mul_f32_e32 v120, v193, v193
	v_fmac_f32_e32 v117, v118, v118
	v_fmac_f32_e32 v120, v192, v192
	v_pk_fma_f32 v[114:115], v[114:115], v[190:191], v[146:147] op_sel_hi:[1,0,1]
	v_add_f32_e32 v117, v117, v120
	v_add_f32_e32 v116, v116, v117
	v_mul_f32_e32 v117, v115, v115
	v_mul_f32_e32 v120, v195, v195
	v_fmac_f32_e32 v117, v114, v114
	v_fmac_f32_e32 v120, v194, v194
	v_add_f32_e32 v117, v117, v120
	v_add_f32_e32 v116, v116, v117
	v_mov_b32_e32 v117, v116
	s_nop 1
	v_permlane16_swap_b32_e32 v116, v117
	v_add_f32_e32 v116, v116, v117
	v_mov_b32_e32 v117, v116
	s_nop 1
	v_permlane32_swap_b32_e32 v116, v117
	v_add_f32_e32 v116, v116, v117
	v_fmamk_f32 v116, v116, 0x3c800000, v223
	v_rsq_f32_e32 v188, v116
	v_mul_f32_e32 v0, 0.15915494, v0
	v_mul_f32_e32 v173, v0, v171
	v_pk_mul_f32 v[116:117], v[126:127], v[188:189] op_sel_hi:[1,0]
	v_pk_mul_f32 v[122:123], v[122:123], v[188:189] op_sel_hi:[1,0]
	v_pk_mul_f32 v[120:121], v[128:129], v[188:189] op_sel_hi:[1,0]
	s_waitcnt vmcnt(3)
	v_pk_mul_f32 v[128:129], v[142:143], v[116:117]
	v_pk_mul_f32 v[116:117], v[124:125], v[188:189] op_sel_hi:[1,0]
	s_waitcnt vmcnt(2)
	v_pk_mul_f32 v[126:127], v[138:139], v[122:123]
	v_pk_mul_f32 v[122:123], v[118:119], v[188:189] op_sel_hi:[1,0]
	v_pk_mul_f32 v[118:119], v[192:193], v[188:189] op_sel_hi:[1,0]
	v_pk_mul_f32 v[124:125], v[114:115], v[188:189] op_sel_hi:[1,0]
	v_pk_mul_f32 v[114:115], v[194:195], v[188:189] op_sel_hi:[1,0]
	v_pk_mul_f32 v[120:121], v[144:145], v[120:121]
	v_pk_mul_f32 v[116:117], v[140:141], v[116:117]
	s_waitcnt vmcnt(1)
	v_pk_mul_f32 v[118:119], v[136:137], v[118:119]
	v_pk_mul_f32 v[122:123], v[134:135], v[122:123]
	s_waitcnt vmcnt(0)
	v_pk_mul_f32 v[114:115], v[132:133], v[114:115]
	v_pk_mul_f32 v[124:125], v[130:131], v[124:125]
	v_mul_f32_e32 v188, v169, v171
	s_cbranch_vccnz .LBB0_662
	v_ashrrev_i32_e32 v190, 6, v216
	v_cvt_f32_i32_e32 v197, v190
	v_mul_f32_e32 v190, v0, v197
	v_mul_f32_e32 v191, v165, v197
	v_mul_f32_e32 v194, v167, v197
	v_floor_f32_e32 v190, v190
	v_floor_f32_e32 v191, v191
	v_floor_f32_e32 v194, v194
	v_mul_f32_e32 v200, v169, v197
	v_fma_f32 v192, v0, v197, -v190
	v_fma_f32 v193, v165, v197, -v191
	v_fma_f32 v194, v167, v197, -v194
	v_floor_f32_e32 v200, v200
	v_sin_f32_e32 v190, v192
	v_sin_f32_e32 v191, v193
	v_cos_f32_e32 v199, v194
	v_sin_f32_e32 v202, v194
	v_fma_f32 v197, v169, v197, -v200
	v_cos_f32_e32 v192, v192
	v_cos_f32_e32 v193, v193
	v_sin_f32_e32 v201, v197
	v_cos_f32_e32 v200, v197
	v_pk_mul_f32 v[194:195], v[190:191], v[126:127]
	v_mul_f32_e32 v198, v202, v116
	v_mul_f32_e32 v204, v199, v116
	v_mov_b32_e32 v116, v121
	v_pk_mul_f32 v[126:127], v[192:193], v[126:127]
	v_mul_f32_e32 v196, v199, v120
	v_mul_f32_e32 v202, v202, v120
	v_pk_mul_f32 v[120:121], v[200:201], v[116:117]
	v_pk_fma_f32 v[192:193], v[192:193], v[128:129], v[194:195] neg_lo:[0,0,1] neg_hi:[0,0,1]
	v_floor_f32_e32 v194, v175
	v_mov_b32_e32 v197, v120
	v_mov_b32_e32 v199, v121
	v_mov_b32_e32 v120, v201
	v_mov_b32_e32 v121, v200
	v_pk_fma_f32 v[126:127], v[190:191], v[128:129], v[126:127]
	v_floor_f32_e32 v128, v173
	v_fma_f32 v194, v167, v171, -v194
	v_floor_f32_e32 v200, v188
	v_pk_mul_f32 v[116:117], v[120:121], v[116:117]
	v_pk_add_f32 v[120:121], v[196:197], v[198:199] neg_lo:[0,1] neg_hi:[0,1]
	v_fma_f32 v129, v0, v171, -v128
	v_cos_f32_e32 v197, v194
	v_sin_f32_e32 v199, v194
	v_fma_f32 v200, v169, v171, -v200
	v_sin_f32_e32 v128, v129
	v_cos_f32_e32 v190, v129
	v_floor_f32_e32 v129, v177
	v_sin_f32_e32 v201, v200
	v_cos_f32_e32 v200, v200
	v_fma_f32 v191, v165, v171, -v129
	v_mov_b32_e32 v203, v116
	v_mov_b32_e32 v205, v117
	v_sin_f32_e32 v129, v191
	v_pk_add_f32 v[116:117], v[202:203], v[204:205]
	v_cos_f32_e32 v191, v191
	v_mul_f32_e32 v198, v199, v114
	v_mul_f32_e32 v204, v197, v114
	v_mov_b32_e32 v114, v119
	v_mul_f32_e32 v196, v197, v118
	v_mul_f32_e32 v202, v199, v118
	v_pk_mul_f32 v[118:119], v[200:201], v[114:115]
	v_pk_mul_f32 v[194:195], v[128:129], v[124:125]
	v_mov_b32_e32 v197, v118
	v_mov_b32_e32 v199, v119
	v_mov_b32_e32 v118, v201
	v_mov_b32_e32 v119, v200
	v_pk_mul_f32 v[114:115], v[118:119], v[114:115]
	v_pk_mul_f32 v[124:125], v[190:191], v[124:125]
	v_mov_b32_e32 v203, v114
	v_mov_b32_e32 v205, v115
	v_pk_fma_f32 v[190:191], v[190:191], v[122:123], v[194:195] neg_lo:[0,0,1] neg_hi:[0,0,1]
	v_pk_add_f32 v[118:119], v[196:197], v[198:199] neg_lo:[0,1] neg_hi:[0,1]
	v_pk_fma_f32 v[124:125], v[128:129], v[122:123], v[124:125]
	v_pk_add_f32 v[114:115], v[202:203], v[204:205]
	v_mov_b32_e32 v128, v192
	v_mov_b32_e32 v129, v193
	v_mov_b32_e32 v122, v190
	v_mov_b32_e32 v123, v191
